# v18: v17 + hg2 forward state tile requested one item ahead
# speedup vs baseline: 1.0058x; 1.0058x over previous
; #define SP_BEGIN() unsigned long long sp0_ = 0; if (PROBE_MASK >> 16) sp0_ = __builtin_amdgcn_s_memrealtime();
; template <bool RET> __device__ __forceinline__ void out_load(const Ctx& X, const bf16* H, int r, OutRegs<RET>& R) {
;     const int b = r / 768, head = (r / 128) % 6, n = r % 128; const size_t m0 = (size_t)(b * SEQ + n * CH);
;     const int fr = X.lane & 15, fq = X.lane >> 4, tb = X.wave & 3, vh = X.wave >> 2; const size_t m = m0 + 16 * tb + fr; const int gcol = (RET ? C_RG : C_HGG) + head * 128;
;     raw_load<128>(X, H, m0, (RET ? C_RV : C_HGV) + head * 128, R.rv);
;     if (!RET) { raw_load<128>(X, H, m0, C_ZF + head * 128, R.rzf); raw_load<128>(X, H, m0, C_HGQ + head * 128, R.rq); }
;     else { raw_load<64>(X, H, m0, C_RQ + head * 64, R.rq6); raw_load<64>(X, H, m0, C_RK + head * 64, R.rk6); }
; #pragma unroll
;     for (int t = 0; t < 4; ++t) if (RET) R.gw[t] = *(const v2u*)hptr(H, m, gcol + 64 * vh + 16 * t + 4 * fq);
; }
; template <int DK, bool RET>
; __device__ __forceinline__ void gla_out_item(const Ctx& X, const bf16* H, bf16* Y, int l, int r, OutRegs<RET>& R, bool has_next) {
;     typedef L3<DK, RET> L;
;     const int b = r / 768, head = (r / 128) % 6, n = r % 128;
;     const float* LB = (const float*)(X.ws + WS_TAB);
;     const unsigned char* St = (const unsigned char*)(X.ws + WS_SHG);
;     const int fr = X.lane & 15, fq = X.lane >> 4, tb = X.wave & 3, vh = X.wave >> 2;
;     const size_t m = (size_t)(b * SEQ + n * CH + 16 * tb + fr);
;     const int ycol = (RET ? 768 : 0) + head * 128;
;     SP_BEGIN()
;     const int kp = X.tid & 63; f32x2v lb0 = (f32x2v){0.f, 0.f}, lb1 = lb0;
;     v2u gw[4];
;     if (!RET) {
;         lb0 = *(const f32x2v*)(LB + (0 * 4 + l) * 768 + head * 128 + 2 * kp); lb1 = *(const f32x2v*)(LB + (1 * 4 + l) * 768 + head * 128 + 2 * kp);
;         vt_store(X, X.lds + L::VT, R.rv); raw_store<128>(X, X.lds + L::RAW, R.rzf); raw_store<128>(X, X.lds + L::RAW + 16384, R.rq);
.LBB0_474:
	s_andn2_b64 vcc, exec, s[0:1]
	s_cbranch_vccnz .LBB0_651
	v_readlane_b32 s18, v253, 0
	v_readlane_b32 s0, v253, 6
	v_mov_b32_e32 v42, v0
	v_readlane_b32 s19, v253, 1
	v_readlane_b32 s1, v253, 7
	s_waitcnt lgkmcnt(0)
	s_load_dword s87, s[0:1], 0x0
	v_readlane_b32 s0, v254, 15
	v_readlane_b32 s1, v254, 16
	v_readfirstlane_b32 s4, v42
	s_andn2_b64 vcc, exec, s[0:1]
	s_mul_i32 s34, s86, 0x300
	s_cbranch_vccnz .LBB0_566
	v_ashrrev_i32_e32 v43, 31, v42
	s_waitcnt vmcnt(0)
	v_lshrrev_b32_e32 v2, 28, v43
	v_add_u32_e32 v2, v42, v2
	v_ashrrev_i32_e32 v44, 4, v2
	v_and_b32_e32 v2, 0x1ffffff0, v2
	v_add_u32_e32 v28, 0x200, v42
	v_sub_u32_e32 v2, v42, v2
	v_ashrrev_i32_e32 v29, 31, v28
	s_waitcnt lgkmcnt(0)
	v_lshlrev_b32_e32 v47, 3, v2
	v_lshrrev_b32_e32 v2, 28, v29
	s_load_dwordx2 s[0:1], s[18:19], 0x78
	v_add_u32_e32 v2, v28, v2
	v_ashrrev_i32_e32 v48, 4, v2
	v_and_b32_e32 v2, 0x1ffffff0, v2
	v_readlane_b32 s12, v254, 9
	v_sub_u32_e32 v2, v28, v2
	v_ashrrev_i32_e32 v49, 31, v48
	v_readlane_b32 s13, v254, 10
	v_lshlrev_b32_e32 v112, 3, v2
	v_readlane_b32 s5, v254, 13
	v_lshl_add_u64 v[4:5], v[48:49], 0, s[12:13]
	v_lshlrev_b64 v[18:19], 8, v[4:5]
	v_add_u32_e32 v2, s5, v112
	v_add_u32_e32 v4, s5, v47
	v_readlane_b32 s5, v254, 12
	s_waitcnt lgkmcnt(0)
	s_add_u32 s75, s0, 0x21800000
	s_addc_u32 s76, s1, 0
	v_add_u32_e32 v10, s5, v112
	v_add_u32_e32 v12, s5, v47
	v_readlane_b32 s5, v254, 11
	v_ashrrev_i32_e32 v2, 7, v2
	s_add_u32 s24, s0, 0x25800000
	v_add_u32_e32 v24, s5, v112
	v_ashrrev_i32_e32 v3, 31, v2
	v_lshrrev_b32_e32 v10, 7, v10
	v_mov_b32_e32 v11, v159
	v_lshrrev_b32_e32 v24, 7, v24
	v_mov_b32_e32 v25, v159
	s_addc_u32 s25, s1, 0
	v_lshlrev_b64 v[2:3], 22, v[2:3]
	v_lshlrev_b64 v[10:11], 22, v[10:11]
	v_lshlrev_b64 v[24:25], 22, v[24:25]
	v_and_b32_e32 v26, 0x78, v112
	v_lshl_add_u64 v[2:3], s[24:25], 0, v[2:3]
	v_lshl_add_u64 v[10:11], s[24:25], 0, v[10:11]
	v_lshl_add_u64 v[24:25], s[24:25], 0, v[24:25]
	v_lshl_add_u64 v[2:3], v[2:3], 0, v[18:19]
	v_lshlrev_b32_e32 v158, 1, v26
	v_ashrrev_i32_e32 v4, 7, v4
	v_lshl_add_u64 v[10:11], v[10:11], 0, v[18:19]
	v_lshl_add_u64 v[18:19], v[24:25], 0, v[18:19]
	v_add_u32_e32 v24, s5, v47
	v_ashrrev_i32_e32 v45, 31, v44
	v_lshl_add_u64 v[2:3], v[2:3], 0, v[158:159]
	v_ashrrev_i32_e32 v5, 31, v4
	v_lshl_add_u64 v[10:11], v[10:11], 0, v[158:159]
	v_lshrrev_b32_e32 v12, 7, v12
	v_mov_b32_e32 v13, v159
	v_lshl_add_u64 v[18:19], v[18:19], 0, v[158:159]
	v_lshrrev_b32_e32 v158, 7, v24
	v_lshlrev_b64 v[4:5], 22, v[4:5]
	v_lshl_add_u64 v[6:7], v[44:45], 0, s[12:13]
	v_lshlrev_b64 v[12:13], 22, v[12:13]
	v_lshlrev_b64 v[24:25], 22, v[158:159]
	v_and_b32_e32 v46, 0x78, v47
	v_lshl_add_u64 v[4:5], s[24:25], 0, v[4:5]
	v_lshlrev_b64 v[20:21], 8, v[6:7]
	v_lshl_add_u64 v[12:13], s[24:25], 0, v[12:13]
	v_lshl_add_u64 v[24:25], s[24:25], 0, v[24:25]
	v_lshl_add_u64 v[4:5], v[4:5], 0, v[20:21]
	v_lshlrev_b32_e32 v22, 1, v46
	v_mov_b32_e32 v23, v159
	v_lshl_add_u64 v[12:13], v[12:13], 0, v[20:21]
	v_lshl_add_u64 v[20:21], v[24:25], 0, v[20:21]
	v_lshl_add_u64 v[6:7], v[4:5], 0, v[22:23]
	v_lshl_add_u64 v[14:15], v[12:13], 0, v[22:23]
	v_lshl_add_u64 v[22:23], v[20:21], 0, v[22:23]
	global_load_dwordx4 v[2:5], v[2:3], off
	s_nop 0
	global_load_dwordx4 v[6:9], v[6:7], off
	s_nop 0
	global_load_dwordx4 v[10:13], v[10:11], off
	s_nop 0
	global_load_dwordx4 v[14:17], v[14:15], off
	s_nop 0
	global_load_dwordx4 v[18:21], v[18:19], off
	s_nop 0
	global_load_dwordx4 v[22:25], v[22:23], off
	s_ashr_i32 s5, s4, 6
	s_add_u32 s77, s0, 0x3a800000
	s_addc_u32 s78, s1, 0
	s_lshl_b32 s12, s5, 4
	s_lshl_b64 s[28:29], s[34:35], 2
	s_add_u32 s0, s0, s28
	v_lshlrev_b32_e32 v34, 3, v42
	s_addc_u32 s1, s1, s29
	v_and_b32_e32 v158, 0x1f8, v34
	v_lshl_add_u64 v[30:31], s[0:1], 0, v[158:159]
	s_mov_b64 s[0:1], 0x400000
	v_lshl_add_u64 v[50:51], v[30:31], 0, s[0:1]
	s_mov_b64 s[0:1], 0x403000
	v_and_b32_e32 v33, 15, v42
	v_lshl_add_u64 v[52:53], v[30:31], 0, s[0:1]
	s_movk_i32 s0, 0x480
	v_mad_u32_u24 v30, v33, s0, 0
	s_lshl_b32 s0, s5, 1
	s_ashr_i32 s13, s4, 7
	s_and_b32 s0, s0, 2
	s_cmp_le_i32 s0, s13
	s_cselect_b64 s[36:37], -1, 0
	s_xor_b32 s1, s0, s13
	s_cmp_lt_u32 s1, 2
	v_readlane_b32 s22, v252, 6
	v_readlane_b32 s23, v252, 7
	s_cselect_b32 s1, s22, s23
	s_lshl_b32 s14, s0, 4
	s_cmp_eq_u32 s13, s0
	v_mov_b32_e32 v39, s1
	s_cselect_b64 s[40:41], -1, 0
	s_lshl_b32 s1, s0, 5
	v_readlane_b32 s17, v252, 8
	s_add_i32 s1, s17, s1
	s_or_b32 s15, s0, 1
	s_cmp_lt_i32 s0, s13
	v_ashrrev_i32_e32 v35, 4, v28
	v_lshlrev_b64 v[56:57], 4, v[28:29]
	v_lshrrev_b32_e32 v28, 3, v28
	s_cselect_b64 s[38:39], -1, 0
	s_cmp_ge_i32 s0, s13
	v_bfe_u32 v29, v42, 4, 2
	v_readlane_b32 s60, v252, 5
	v_mul_lo_u32 v28, v28, s27
	s_cselect_b64 s[66:67], -1, 0
	s_lshl_b32 s16, s15, 4
	v_add_u32_e32 v37, s60, v28
	v_lshlrev_b32_e32 v28, 3, v29
	v_lshl_or_b32 v41, s13, 4, v33
	s_cmp_eq_u32 s13, s15
	v_mul_lo_u32 v58, v41, s27
	v_add_u32_e32 v63, s1, v28
	s_cselect_b64 s[48:49], -1, 0
	s_and_b32 s5, s5, 3
	s_lshl_b32 s1, s15, 5
	v_add_u32_e32 v61, 0, v58
	s_add_i32 s1, s17, s1
	v_lshl_or_b32 v60, s5, 4, v33
	v_mov_b32_e32 v58, s17
	s_movk_i32 s20, 0x90
	s_and_b32 s17, s12, 0xffffffc0
	v_mad_u32_u24 v118, v60, s20, v58
	v_or_b32_e32 v58, s17, v33
	v_mul_lo_u32 v62, v58, s20
	v_add_u32_e32 v64, s1, v28
	v_add_u32_e32 v65, 0, v62
	v_and_b32_e32 v62, 8, v42
	v_or_b32_e32 v67, 16, v33
	v_or_b32_e32 v70, 32, v33
	v_or_b32_e32 v73, 48, v33
; #define SP_BEGIN() unsigned long long sp0_ = 0; if (PROBE_MASK >> 16) sp0_ = __builtin_amdgcn_s_memrealtime();
; template <int DK, bool RET, int DIR>
; __device__ __forceinline__ void gla_out_dir(const Ctx& X, int chain, int n, f32x2v lb, const unsigned char* St, f32x4 (&o)[4], const bf16* H, size_t m0, int zbcol) {
;     ...
;     const unsigned char* Sp = St + ((size_t)chain * NCH + n) * 128 * DK;
;     v4u sr[2];
; #pragma unroll
;     for (int p = 0; p < 2; ++p) { const int idx = X.tid + NTHR * p; sr[p] = *(const v4u*)(Sp + (size_t)idx * 16); }
; template <int DK, bool RET>
; __device__ __forceinline__ void gla_out_item(const Ctx& X, const bf16* H, bf16* Y, int l, int r, OutRegs<RET>& R, bool has_next) {
;     typedef L3<DK, RET> L;
;     const int b = r / 768, head = (r / 128) % 6, n = r % 128;
;     const float* LB = (const float*)(X.ws + WS_TAB);
;     const unsigned char* St = (const unsigned char*)(X.ws + WS_SHG);
;     const int fr = X.lane & 15, fq = X.lane >> 4, tb = X.wave & 3, vh = X.wave >> 2;
;     const size_t m = (size_t)(b * SEQ + n * CH + 16 * tb + fr);
;     const int ycol = (RET ? 768 : 0) + head * 128;
;     SP_BEGIN()
;     const int kp = X.tid & 63; f32x2v lb0 = (f32x2v){0.f, 0.f}, lb1 = lb0;
;     v2u gw[4];
;     if (!RET) {
;         lb0 = *(const f32x2v*)(LB + (0 * 4 + l) * 768 + head * 128 + 2 * kp); lb1 = *(const f32x2v*)(LB + (1 * 4 + l) * 768 + head * 128 + 2 * kp);
;         vt_store(X, X.lds + L::VT, R.rv); raw_store<128>(X, X.lds + L::RAW, R.rzf); raw_store<128>(X, X.lds + L::RAW + 16384, R.rq);
	s_sub_i32 s1, 3, s13
	v_bitop3_b32 v66, v28, v42, 8 bitop3:0x78
	v_bitop3_b32 v69, v67, v28, 24 bitop3:0x6c
	v_bitop3_b32 v72, v70, v28, 40 bitop3:0x6c
	v_bitop3_b32 v75, v73, v28, 56 bitop3:0x6c
	v_or_b32_e32 v76, 32, v28
	v_bitop3_b32 v28, v28, v62, 32 bitop3:0x36
	s_xor_b32 s0, s1, s0
	v_lshlrev_b32_e32 v78, 1, v28
	v_bitop3_b32 v28, v67, v76, 24 bitop3:0x6c
	s_xor_b32 s0, s0, 2
	v_lshlrev_b32_e32 v67, 1, v28
	v_bitop3_b32 v28, v70, v76, 40 bitop3:0x6c
	s_cmp_lt_u32 s0, 2
	v_lshlrev_b32_e32 v70, 1, v28
	v_bitop3_b32 v28, v73, v76, 56 bitop3:0x6c
	s_cselect_b64 s[58:59], -1, 0
	v_lshlrev_b32_e32 v73, 1, v28
	v_or_b32_e32 v28, 0xffffffe0, v33
	s_and_b64 s[0:1], s[58:59], exec
	v_or_b32_e32 v38, s14, v33
	v_add_u32_e32 v62, s14, v28
	s_cselect_b32 s14, s22, s23
	s_cmp_le_i32 s13, s15
	s_cselect_b64 s[30:31], -1, 0
	s_cmp_lt_u32 s5, 2
	s_cselect_b64 s[50:51], -1, 0
	s_and_b64 s[0:1], s[50:51], exec
	v_readlane_b32 s1, v252, 9
	v_mad_u32_u24 v40, v38, s27, v39
	v_cndmask_b32_e64 v38, v62, v38, s[58:59]
	v_subrev_u32_e32 v62, 32, v60
	s_cselect_b32 s0, 0, s1
	v_lshlrev_b32_e32 v77, 1, v76
	v_cndmask_b32_e64 v62, v62, v60, s[50:51]
	v_mov_b32_e32 v76, s0
	v_ashrrev_i32_e32 v31, 4, v42
	v_lshlrev_b32_e32 v29, 2, v29
	v_or_b32_e32 v59, s16, v33
	v_mad_i32_i24 v62, v62, s27, v76
	v_mul_lo_u32 v76, v58, s27
	v_lshrrev_b32_e32 v58, 2, v42
	v_add_u32_e32 v28, s16, v28
	v_and_b32_e32 v27, 63, v42
	v_readlane_b32 s21, v252, 4
	v_bitop3_b32 v31, v34, v31, 56 bitop3:0x6c
	v_bitop3_b32 v34, v35, v34, 56 bitop3:0x78
	v_lshrrev_b32_e32 v35, 3, v42
	v_sub_u32_e32 v29, v33, v29
	v_and_or_b32 v58, v58, 12, s17
	v_mov_b32_e32 v80, s14
	v_cndmask_b32_e64 v28, v28, v59, s[58:59]
	s_cselect_b32 s0, s1, 0
	s_andn2_b32 s4, s4, 63
	v_lshl_add_u32 v32, v27, 2, s21
	v_and_or_b32 v113, s12, 48, v33
	v_lshlrev_b64 v[54:55], 4, v[42:43]
	v_mul_lo_u32 v35, v35, s27
	v_lshlrev_b32_e32 v36, 5, v42
	v_and_b32_e32 v43, 48, v42
	v_cmp_gt_i32_e64 s[42:43], 0, v29
	v_cmp_gt_i32_e64 s[44:45], 1, v29
	v_cmp_gt_i32_e64 s[46:47], 2, v29
	v_cmp_gt_i32_e32 vcc, 3, v29
	v_add_u32_e32 v119, 0xc00, v58
	v_cmp_lt_i32_e64 s[50:51], 0, v29
	v_cmp_lt_i32_e64 s[52:53], 1, v29
	v_cmp_lt_i32_e64 s[54:55], 2, v29
	v_cmp_lt_i32_e64 s[56:57], 3, v29
	v_mad_i32_i24 v29, v28, s27, v80
	v_mov_b32_e32 v28, s0
	v_cmp_gt_u32_e64 s[58:59], 16, v27
	s_add_i32 s0, s21, s4
	v_bitop3_b32 v27, s12, 64, v33 bitop3:0x36
	v_lshlrev_b32_e32 v123, 1, v58
	v_lshlrev_b32_e32 v31, 1, v31
	v_lshlrev_b32_e32 v34, 1, v34
	v_add_u32_e32 v35, s60, v35
	v_and_b32_e32 v36, 0xe0, v36
	v_mad_u32_u24 v39, v59, s27, v39
	v_lshlrev_b32_e32 v66, 1, v66
	v_add_u32_e32 v68, 0x900, v65
	v_lshlrev_b32_e32 v69, 1, v69
	v_add_u32_e32 v71, 0x1200, v65
	v_lshlrev_b32_e32 v72, 1, v72
	v_add_u32_e32 v74, 0x1b00, v65
	v_lshlrev_b32_e32 v75, 1, v75
	v_add_u32_e32 v79, s60, v43
	v_mad_i32_i24 v38, v38, s27, v80
	v_mad_u32_u24 v80, v60, s27, v28
	v_lshl_add_u32 v120, v33, 2, s0
	v_lshl_add_u32 v121, v27, 2, s21
	v_mad_u32_u24 v122, v113, s27, 0
	v_or_b32_e32 v27, 32, v123
	v_or_b32_e32 v33, 64, v123
	v_or_b32_e32 v81, 0x60, v123
	v_mul_lo_u32 v41, v41, s20
	v_add_u32_e32 v124, s60, v76
	v_and_b32_e32 v28, 0x4c, v119
	v_lshlrev_b32_e32 v114, 4, v42
	v_or_b32_e32 v115, 64, v43
	v_or_b32_e32 v116, 0x80, v43
	v_or_b32_e32 v117, 0xc0, v43
	v_ashrrev_i32_e32 v59, 31, v58
	s_and_b64 s[16:17], s[40:41], vcc
	s_and_b64 s[22:23], s[48:49], vcc
	v_add_u32_e32 v125, 0x1100, v124
	v_add_u32_e32 v126, 0x2200, v124
	v_add_u32_e32 v127, 0x3300, v124
	s_lshl_b32 s79, s87, 6
	v_add_u32_e32 v128, v30, v31
	v_add_u32_e32 v129, v30, v34
	v_lshlrev_b32_e32 v60, 1, v26
	v_add_u32_e32 v130, v40, v43
	v_add_u32_e32 v131, v39, v43
	v_add_u32_e32 v132, v62, v43
	v_lshlrev_b32_e32 v62, 1, v28
	v_add_u32_e32 v133, v38, v43
	v_add_u32_e32 v134, v29, v43
	v_add_u32_e32 v135, v80, v43
	v_add_u32_e32 v136, s4, v32
	v_add_u32_e32 v137, v122, v27
	v_add_u32_e32 v138, v122, v33
	v_add_u32_e32 v139, v122, v81
	v_add_u32_e32 v140, v35, v36
	v_add_u32_e32 v141, v37, v36
	v_add_u32_e32 v142, v61, v43
	v_add_u32_e32 v143, v63, v41
	v_add_u32_e32 v144, v64, v41
	v_add_u32_e32 v145, v65, v66
	v_add_u32_e32 v146, v68, v69
	v_add_u32_e32 v147, v71, v72
	v_add_u32_e32 v148, v74, v75
	v_add_u32_e32 v149, v118, v77
	v_add_u32_e32 v150, v65, v78
	v_add_u32_e32 v151, v68, v67
	v_add_u32_e32 v152, v71, v70
	v_add_u32_e32 v153, v74, v73
	v_add_u32_e32 v154, v79, v76
	v_readlane_b32 s80, v254, 60
	s_mov_b32 s0, s2
	s_load_dwordx2 s[100:101], s[18:19], 0x48
	s_waitcnt lgkmcnt(0)
	s_add_u32 s100, s100, s28
	s_addc_u32 s101, s101, s29
	v_lshl_add_u64 v[242:243], v[58:59], 2, s[100:101]
	s_ashr_i32 s100, s0, 7
	s_mul_hi_i32 s101, s100, 0x2aaaaaab
	s_mul_i32 s101, s101, 6
	s_sub_i32 s100, s100, s101
	s_lshl_b32 s100, s100, 9
	s_mov_b32 s101, 0
	v_lshl_add_u64 v[222:223], v[52:53], 0, s[100:101]
	v_lshl_add_u64 v[224:225], v[50:51], 0, s[100:101]
	global_load_dwordx2 v[222:223], v[222:223], off
	global_load_dwordx2 v[224:225], v[224:225], off
	s_lshr_b32 s100, s0, 7
	s_and_b32 s101, s0, 0x7f
	s_lshl_b32 s101, s101, 14
	s_lshl_b32 s100, s100, 22
	s_add_u32 s100, s100, s101
	s_add_u32 s100, s77, s100
	s_addc_u32 s101, s78, 0
	v_lshl_add_u64 v[250:251], s[100:101], 0, v[54:55]
	global_load_dwordx4 v[188:191], v[250:251], off
	v_lshl_add_u64 v[250:251], s[100:101], 0, v[56:57]
	global_load_dwordx4 v[246:249], v[250:251], off
	s_waitcnt vmcnt(0)
	s_branch .LBB0_478

; template <int DK, bool RET, int DIR>
; __device__ __forceinline__ void gla_out_dir(const Ctx& X, int chain, int n, f32x2v lb, const unsigned char* St, f32x4 (&o)[4], const bf16* H, size_t m0, int zbcol) {
;     ...
;     const unsigned char* Sp = St + ((size_t)chain * NCH + n) * 128 * DK;
;     v4u sr[2];
; #pragma unroll
;     for (int p = 0; p < 2; ++p) { const int idx = X.tid + NTHR * p; sr[p] = *(const v4u*)(Sp + (size_t)idx * 16); }
.LBB0_480:
	s_mul_hi_i32 s60, s0, 0x2aaaaaab
	s_lshr_b32 s61, s60, 31
	s_ashr_i32 s84, s60, 7
	s_lshl_b32 s60, s83, 7
	s_add_i32 s84, s84, s61
	s_sub_i32 s0, s0, s60
	s_mul_i32 s60, s84, 6
	s_add_i32 s60, s60, s1
	s_lshl_b32 s62, s60, 1
	s_ashr_i32 s63, s62, 31
	s_ashr_i32 s1, s0, 31
	s_lshl_b64 s[0:1], s[0:1], 14
	s_lshl_b64 s[68:69], s[62:63], 21
	s_add_u32 s61, s77, s68
	s_addc_u32 s63, s78, s69
	s_add_u32 s68, s61, s0
	s_addc_u32 s69, s63, s1
	v_mov_b32_e32 v35, v42
	s_waitcnt lgkmcnt(0)
	s_barrier
	v_mov_b32_e32 v30, v188
	v_mov_b32_e32 v31, v189
	v_mov_b32_e32 v32, v190
	v_mov_b32_e32 v33, v191
	v_mov_b32_e32 v26, v246
	v_mov_b32_e32 v27, v247
	v_mov_b32_e32 v28, v248
	v_mov_b32_e32 v29, v249
	s_cmp_lg_u64 s[4:5], 0
	s_cbranch_scc1 .Lhg2_nopf
	s_lshr_b32 s100, s81, 7
	s_and_b32 s101, s81, 0x7f
	s_lshl_b32 s101, s101, 14
	s_lshl_b32 s100, s100, 22
	s_add_u32 s100, s100, s101
	s_add_u32 s100, s77, s100
	s_addc_u32 s101, s78, 0
	v_lshl_add_u64 v[250:251], s[100:101], 0, v[54:55]
	global_load_dwordx4 v[188:191], v[250:251], off
	v_lshl_add_u64 v[250:251], s[100:101], 0, v[56:57]
	global_load_dwordx4 v[246:249], v[250:251], off
; #define LAS __attribute__((address_space(3)))
; template <int DIR, bool NEEDQ>
; __device__ __forceinline__ void gla_prep(lptr rawz, lptr rawq, f32x2v lb, LAS float* seg, int kp, int rg, f32x2v (&c)[8], f32x2v (&qv)[8], f32x2v (&kv)[8]) {
;     f32x2v run = (f32x2v){1.f, 1.f}; const f32x2v oml = 1.0f - lb;
; #pragma unroll
;     for (int i = 0; i < 8; ++i) { const int ii = DIR ? 7 - i : i; const int r = 8 * rg + ii;
;         const f32x2v z = bfpair(*(const LAS unsigned*)(rawz + (r * 128 + 2 * kp) * 2)); f32x2v e; e.x = __expf(-z.x); e.y = __expf(-z.y);
;         const f32x2v f = lb + oml * rcp2(e + 1.0f); run = run * f; kv[ii] = 1.0f - f; c[ii] = run;
;         if (NEEDQ) qv[ii] = bfpair(*(const LAS unsigned*)(rawq + (r * 128 + 2 * kp) * 2)); }
;     *(LAS f32x2v*)(seg + rg * 128 + 2 * kp) = run;
; }
; template <int DK, bool RET, int DIR>
; __device__ __forceinline__ void gla_out_dir(const Ctx& X, int chain, int n, f32x2v lb, const unsigned char* St, f32x4 (&o)[4], const bf16* H, size_t m0, int zbcol) {
;     ...
;     const unsigned char* Sp = St + ((size_t)chain * NCH + n) * 128 * DK;
;     v4u sr[2];
; #pragma unroll
;     for (int p = 0; p < 2; ++p) { const int idx = X.tid + NTHR * p; sr[p] = *(const v4u*)(Sp + (size_t)idx * 16); }
;     {
;         f32x2v c[8], qv[8], kv[8];
;         gla_prep<DIR, true>(rawz, rawq, lb, seg, kp, rg, c, qv, kv);
;         BAR_LDS(); SP_END(21);
; #pragma unroll
;         for (int p = 0; p < 2; ++p) { const int idx = X.tid + NTHR * p; const lptr d = ST + (idx >> 3) * 272 + (idx & 7) * 32;
;             v4u a, b; f32x2v f;
;             f = f8lo(sr[p].x); a.x = pk2(f.x, f.y); f = f8hi(sr[p].x); a.y = pk2(f.x, f.y); f = f8lo(sr[p].y); a.z = pk2(f.x, f.y); f = f8hi(sr[p].y); a.w = pk2(f.x, f.y);
;             f = f8lo(sr[p].z); b.x = pk2(f.x, f.y); f = f8hi(sr[p].z); b.y = pk2(f.x, f.y); f = f8lo(sr[p].w); b.z = pk2(f.x, f.y); f = f8hi(sr[p].w); b.w = pk2(f.x, f.y);
;             *(LAS v4u*)d = a; *(LAS v4u*)(d + 16) = b; }
;         {
;             const int sg = DIR ? 7 - rg : rg, ss = sg >> 2, hq = sg & 3;
;             const f32x2v T0 = SEGT(0), T1 = SEGT(1), T2 = SEGT(2), T3 = SEGT(3), sub0 = (T0 * T1) * (T2 * T3);
;             f32x2v pq = (f32x2v){1.f, 1.f};
; #pragma unroll
;             for (int j = 0; j < 3; ++j) if (j < hq) pq = pq * SEGT(4 * ss + j);
.Lhg2_nopf:
	s_add_u32 s98, s68, 0x200000
	s_addc_u32 s99, s69, 0
	v_lshl_add_u64 v[220:221], s[98:99], 0, v[54:55]
	global_load_dwordx4 v[212:215], v[220:221], off
	v_lshl_add_u64 v[220:221], s[98:99], 0, v[56:57]
	global_load_dwordx4 v[216:219], v[220:221], off
	v_readfirstlane_b32 s60, v35
	v_and_b32_e32 v90, 63, v35
	s_ashr_i32 s61, s60, 6
	v_lshlrev_b32_e32 v35, 2, v90
	v_lshl_or_b32 v91, s61, 11, v35
	s_add_i32 s63, 0, 0x14c00
	v_add_u32_e32 v36, s63, v91
	ds_read_b32 v36, v36
	s_add_i32 s82, 0, 0x18c00
	v_or_b32_e32 v40, 0x100, v91
	v_or_b32_e32 v68, 0x200, v91
	v_or_b32_e32 v74, 0x300, v91
	s_waitcnt lgkmcnt(0)
	v_lshlrev_b32_e32 v37, 16, v36
	v_and_b32_e32 v38, 0xffff0000, v36
	v_mul_f32_e32 v36, 0xbfb8aa3b, v37
	v_mul_f32_e32 v37, 0xbfb8aa3b, v38
	v_add_u32_e32 v38, s82, v91
	v_or_b32_e32 v78, 0x400, v91
	v_or_b32_e32 v80, 0x500, v91
	v_or_b32_e32 v96, 0x600, v91
	v_or_b32_e32 v91, 0x700, v91
	v_add_u32_e32 v98, s63, v91
	ds_read_b32 v61, v38
	ds_read_b32 v98, v98
	v_add_u32_e32 v38, s63, v40
	v_add_u32_e32 v40, s82, v40
	ds_read_b32 v38, v38
	ds_read_b32 v93, v40
	v_add_u32_e32 v40, s63, v68
	v_add_u32_e32 v68, s82, v68
	ds_read_b32 v40, v40
	ds_read_b32 v92, v68
	v_add_u32_e32 v68, s63, v74
	v_add_u32_e32 v74, s82, v74
	ds_read_b32 v68, v68
	ds_read_b32 v94, v74
	v_add_u32_e32 v74, s63, v78
	v_add_u32_e32 v78, s82, v78
	ds_read_b32 v74, v74
	ds_read_b32 v95, v78
	v_add_u32_e32 v78, s63, v80
	v_add_u32_e32 v80, s82, v80
	ds_read_b32 v78, v78
	ds_read_b32 v97, v80
	v_add_u32_e32 v80, s63, v96
	s_waitcnt lgkmcnt(9)
	v_lshlrev_b32_e32 v39, 16, v38
	v_and_b32_e32 v41, 0xffff0000, v38
	ds_read_b32 v80, v80
	v_mul_f32_e32 v38, 0xbfb8aa3b, v39
	v_mul_f32_e32 v39, 0xbfb8aa3b, v41
	s_waitcnt lgkmcnt(8)
	v_lshlrev_b32_e32 v41, 16, v40
	v_and_b32_e32 v64, 0xffff0000, v40
	v_exp_f32_e32 v36, v36
	v_exp_f32_e32 v37, v37
	v_exp_f32_e32 v38, v38
	v_exp_f32_e32 v39, v39
	v_mul_f32_e32 v40, 0xbfb8aa3b, v41
	v_mul_f32_e32 v41, 0xbfb8aa3b, v64
	s_waitcnt lgkmcnt(6)
	v_lshlrev_b32_e32 v69, 16, v68
	v_and_b32_e32 v72, 0xffff0000, v68
	v_exp_f32_e32 v40, v40
	v_exp_f32_e32 v41, v41
	v_mul_f32_e32 v68, 0xbfb8aa3b, v69
	v_mul_f32_e32 v69, 0xbfb8aa3b, v72
	s_waitcnt lgkmcnt(4)
	v_lshlrev_b32_e32 v75, 16, v74
	v_and_b32_e32 v76, 0xffff0000, v74
	v_exp_f32_e32 v68, v68
	v_exp_f32_e32 v69, v69
	v_mul_f32_e32 v74, 0xbfb8aa3b, v75
	v_mul_f32_e32 v75, 0xbfb8aa3b, v76
	s_waitcnt lgkmcnt(2)
	v_lshlrev_b32_e32 v79, 16, v78
	v_and_b32_e32 v81, 0xffff0000, v78
	v_add_u32_e32 v96, s82, v96
	v_exp_f32_e32 v74, v74
	v_exp_f32_e32 v75, v75
	v_mul_f32_e32 v78, 0xbfb8aa3b, v79
	v_mul_f32_e32 v79, 0xbfb8aa3b, v81
	ds_read_b32 v96, v96
	s_waitcnt lgkmcnt(1)
	v_lshlrev_b32_e32 v81, 16, v80
	v_and_b32_e32 v82, 0xffff0000, v80
	v_pk_add_f32 v[36:37], v[36:37], 1.0 op_sel_hi:[1,0]
	v_pk_add_f32 v[38:39], v[38:39], 1.0 op_sel_hi:[1,0]
	v_exp_f32_e32 v78, v78
	v_exp_f32_e32 v79, v79
	v_mul_f32_e32 v80, 0xbfb8aa3b, v81
	v_mul_f32_e32 v81, 0xbfb8aa3b, v82
	v_lshlrev_b32_e32 v99, 16, v98
	v_and_b32_e32 v100, 0xffff0000, v98
	v_rcp_f32_e32 v36, v36
	v_rcp_f32_e32 v37, v37
	v_rcp_f32_e32 v38, v38
	v_rcp_f32_e32 v39, v39
	v_pk_add_f32 v[40:41], v[40:41], 1.0 op_sel_hi:[1,0]
	v_exp_f32_e32 v80, v80
	v_exp_f32_e32 v81, v81
	v_mul_f32_e32 v98, 0xbfb8aa3b, v99
	v_mul_f32_e32 v99, 0xbfb8aa3b, v100
	v_rcp_f32_e32 v40, v40
	v_rcp_f32_e32 v41, v41
	v_pk_add_f32 v[68:69], v[68:69], 1.0 op_sel_hi:[1,0]
	v_exp_f32_e32 v98, v98
	v_exp_f32_e32 v99, v99
	v_rcp_f32_e32 v68, v68
	v_rcp_f32_e32 v69, v69
	v_pk_add_f32 v[74:75], v[74:75], 1.0 op_sel_hi:[1,0]
	v_pk_add_f32 v[88:89], v[86:87], 1.0 op_sel_hi:[1,0] neg_lo:[1,0] neg_hi:[1,0]
	v_rcp_f32_e32 v74, v74
	v_rcp_f32_e32 v75, v75
	v_pk_add_f32 v[78:79], v[78:79], 1.0 op_sel_hi:[1,0]
	v_pk_fma_f32 v[36:37], v[88:89], v[36:37], v[86:87]
	v_pk_fma_f32 v[70:71], v[88:89], v[38:39], v[86:87]
	v_rcp_f32_e32 v78, v78
	v_rcp_f32_e32 v79, v79
	v_pk_add_f32 v[80:81], v[80:81], 1.0 op_sel_hi:[1,0]
	v_pk_mul_f32 v[38:39], v[36:37], v[70:71]
	v_pk_fma_f32 v[64:65], v[88:89], v[40:41], v[86:87]
	v_rcp_f32_e32 v80, v80
	v_rcp_f32_e32 v81, v81
	v_pk_add_f32 v[98:99], v[98:99], 1.0 op_sel_hi:[1,0]
	v_pk_mul_f32 v[40:41], v[38:39], v[64:65]
	v_pk_fma_f32 v[72:73], v[88:89], v[68:69], v[86:87]
	v_rcp_f32_e32 v98, v98
	v_rcp_f32_e32 v99, v99
	v_pk_mul_f32 v[68:69], v[40:41], v[72:73]
	v_pk_fma_f32 v[76:77], v[88:89], v[74:75], v[86:87]
	v_pk_fma_f32 v[84:85], v[88:89], v[78:79], v[86:87]
	v_pk_mul_f32 v[74:75], v[68:69], v[76:77]
	v_pk_fma_f32 v[82:83], v[88:89], v[80:81], v[86:87]
	v_pk_mul_f32 v[78:79], v[74:75], v[84:85]
	s_lshl_b32 s68, s61, 9
	v_pk_mul_f32 v[80:81], v[78:79], v[82:83]
	v_pk_fma_f32 v[88:89], v[88:89], v[98:99], v[86:87]
	s_add_i32 s68, s74, s68
	v_lshlrev_b32_e32 v99, 3, v90
	v_pk_mul_f32 v[86:87], v[80:81], v[88:89]
	v_add_u32_e32 v91, s82, v91
	v_add_u32_e32 v90, s68, v99
	ds_read_b32 v98, v91
	ds_write_b64 v90, v[86:87]
	v_cvt_pk_f32_fp8_e32 v[90:91], v30
	s_waitcnt lgkmcnt(0)
	s_barrier
	v_cvt_pk_bf16_f32 v100, v90, v91
	v_cvt_pk_f32_fp8_sdwa v[90:91], v30 src0_sel:WORD_1
	s_and_b32 s68, s61, 3
	s_and_b32 s69, s61, -4
	s_cmp_eq_u32 s68, 0
	v_cvt_pk_bf16_f32 v101, v90, v91
	v_cvt_pk_f32_fp8_e32 v[90:91], v31
	v_cvt_pk_f32_fp8_sdwa v[30:31], v31 src0_sel:WORD_1
	v_cvt_pk_bf16_f32 v102, v90, v91
	v_cvt_pk_bf16_f32 v103, v30, v31
	v_cvt_pk_f32_fp8_e32 v[30:31], v32
	v_cvt_pk_f32_fp8_sdwa v[90:91], v32 src0_sel:WORD_1
	v_cvt_pk_bf16_f32 v30, v30, v31
	v_cvt_pk_bf16_f32 v31, v90, v91
	v_cvt_pk_f32_fp8_e32 v[90:91], v33
	v_cvt_pk_bf16_f32 v32, v90, v91
	v_cvt_pk_f32_fp8_sdwa v[90:91], v33 src0_sel:WORD_1
	v_cvt_pk_bf16_f32 v33, v90, v91
	ds_write_b128 v140, v[100:103]
	ds_write_b128 v140, v[30:33] offset:16
	v_cvt_pk_f32_fp8_e32 v[30:31], v26
	v_cvt_pk_f32_fp8_sdwa v[32:33], v26 src0_sel:WORD_1
	v_cvt_pk_f32_fp8_sdwa v[90:91], v28 src0_sel:WORD_1
	v_cvt_pk_bf16_f32 v30, v30, v31
	v_cvt_pk_bf16_f32 v31, v32, v33
	v_cvt_pk_f32_fp8_e32 v[32:33], v27
	v_cvt_pk_f32_fp8_sdwa v[26:27], v27 src0_sel:WORD_1
	v_cvt_pk_bf16_f32 v32, v32, v33
	v_cvt_pk_bf16_f32 v33, v26, v27
	v_cvt_pk_f32_fp8_e32 v[26:27], v28
	v_cvt_pk_bf16_f32 v26, v26, v27
	v_cvt_pk_bf16_f32 v27, v90, v91
	v_cvt_pk_f32_fp8_e32 v[90:91], v29
	v_cvt_pk_bf16_f32 v28, v90, v91
	v_cvt_pk_f32_fp8_sdwa v[90:91], v29 src0_sel:WORD_1
	v_cvt_pk_bf16_f32 v29, v90, v91
	ds_write_b128 v141, v[30:33]
	ds_write_b128 v141, v[26:29] offset:16
	v_add_u32_e32 v29, 0, v99
	v_add_u32_e32 v28, s74, v99
	v_add_u32_e32 v30, 0x13a00, v29
	v_add_u32_e32 v32, 0x13c00, v29
	v_add_u32_e32 v29, 0x13e00, v29
	ds_read_b64 v[26:27], v28
	ds_read_b64 v[30:31], v30
	ds_read_b64 v[32:33], v32
	ds_read_b64 v[90:91], v29
	v_lshl_add_u32 v99, s69, 9, v28
	s_cbranch_scc1 .LBB0_564
	ds_read_b64 v[28:29], v99
	s_cmp_lt_u32 s68, 2
	s_cbranch_scc1 .LBB0_483
